# adds FoX MFMA-block edits (ballot trim, P.V test/base at loop head, first P.V reads in QK^T tail) to barrier removal + MLA loop-edge; attention epilogue edit dropped
# speedup vs baseline: 1.0029x; 1.0029x over previous
.LBB0_573:
	s_add_i32 s7, s69, s0
	s_cmp_lt_i32 s7, 0
	s_cselect_b64 s[4:5], -1, 0
	s_add_i32 s8, s68, s86
	s_add_i32 s9, s8, 0xffffff80
	s_cmp_le_i32 s9, s95
	s_cselect_b64 s[10:11], -1, 0
	s_or_b64 s[10:11], s[4:5], s[10:11]
	s_andn2_b64 s[4:5], exec, s[10:11]
	s_add_i32 s9, s7, -1
	s_cmp_gt_i32 s9, -1
	s_cselect_b64 s[14:15], -1, 0
	s_add_i32 s9, s8, 0xffffff40
	s_cmp_gt_i32 s9, s95
	s_cselect_b64 s[12:13], -1, 0
	s_and_b64 s[14:15], s[14:15], s[12:13]
	s_cmp_eq_u32 s0, 0
	s_cselect_b64 s[12:13], -1, 0
	s_or_b64 s[14:15], s[14:15], s[12:13]
	v_lshl_add_u32 v254, s6, 14, v202
	s_andn2_b64 vcc, exec, s[10:11]
	s_cbranch_vccnz .LBB0_575
	s_mul_i32 s9, s1, 0x6000
	v_add_u32_e32 v14, s9, v193
	ds_read_b128 v[2:5], v14 offset:0
	ds_read_b128 v[6:9], v14 offset:0x2000
	v_add_u32_e32 v15, s9, v195
	ds_read_b128 v[10:13], v15 offset:0
	ds_read_b128 v[174:177], v15 offset:0x2000
	v_add_u32_e32 v159, s9, v197
	ds_read_b128 v[178:181], v159 offset:0
	s_waitcnt lgkmcnt(4)
	v_add_u32_e32 v163, s9, v199
	v_mfma_f32_32x32x16_bf16 v[96:111], v[2:5], v[112:115], 0
	ds_read_b128 v[2:5], v159 offset:0x2000
	s_waitcnt lgkmcnt(4)
	s_nop 0
	v_mfma_f32_32x32x16_bf16 v[80:95], v[6:9], v[112:115], 0
	ds_read_b128 v[6:9], v163 offset:0
	s_waitcnt lgkmcnt(4)
	s_nop 0
	v_mfma_f32_32x32x16_bf16 v[96:111], v[10:13], v[116:119], v[96:111]
	ds_read_b128 v[10:13], v163 offset:0x2000
	s_waitcnt lgkmcnt(4)
	s_nop 0
	v_mfma_f32_32x32x16_bf16 v[80:95], v[174:177], v[116:119], v[80:95]
	ds_read_b128 v[174:177], v14 offset:0x80
	ds_read_b128 v[208:211], v156 offset:0
	s_waitcnt lgkmcnt(5)
	s_nop 0
	v_mfma_f32_32x32x16_bf16 v[96:111], v[178:181], v[120:123], v[96:111]
	ds_read_b128 v[178:181], v14 offset:0x2080
	s_waitcnt lgkmcnt(5)
	s_nop 0
	v_mfma_f32_32x32x16_bf16 v[80:95], v[2:5], v[120:123], v[80:95]
	ds_read_b128 v[2:5], v15 offset:0x80
	ds_read_b128 v[212:215], v156 offset:0x400
	s_waitcnt lgkmcnt(6)
	s_nop 0
	v_mfma_f32_32x32x16_bf16 v[96:111], v[6:9], v[124:127], v[96:111]
	ds_read_b128 v[6:9], v15 offset:0x2080
	s_waitcnt lgkmcnt(6)
	s_nop 0
	v_mfma_f32_32x32x16_bf16 v[80:95], v[10:13], v[124:127], v[80:95]
	ds_read_b128 v[10:13], v159 offset:0x80
	ds_read_b128 v[216:219], v156 offset:0x800
	s_waitcnt lgkmcnt(6)
	s_nop 0
	v_mfma_f32_32x32x16_bf16 v[96:111], v[174:177], v[208:211], v[96:111]
	ds_read_b128 v[174:177], v159 offset:0x2080
	s_waitcnt lgkmcnt(6)
	s_nop 0
	v_mfma_f32_32x32x16_bf16 v[80:95], v[178:181], v[208:211], v[80:95]
	ds_read_b128 v[178:181], v163 offset:0x80
	ds_read_b128 v[208:211], v156 offset:0xc00
	s_waitcnt lgkmcnt(6)
	s_nop 0
	v_mfma_f32_32x32x16_bf16 v[96:111], v[2:5], v[212:215], v[96:111]
	ds_read_b128 v[2:5], v163 offset:0x2080
	ds_read_b64_tr_b16 v[230:231], v254 offset:0
	ds_read_b64_tr_b16 v[232:233], v254 offset:0x800
	s_waitcnt lgkmcnt(8)
	v_mfma_f32_32x32x16_bf16 v[80:95], v[6:9], v[212:215], v[80:95]
	ds_read_b64_tr_b16 v[234:235], v254 offset:0x1000
	ds_read_b64_tr_b16 v[236:237], v254 offset:0x1800
	s_waitcnt lgkmcnt(8)
	v_mfma_f32_32x32x16_bf16 v[96:111], v[10:13], v[216:219], v[96:111]
	ds_read_b64_tr_b16 v[238:239], v254 offset:0x2000
	ds_read_b64_tr_b16 v[240:241], v254 offset:0x2800
	s_waitcnt lgkmcnt(9)
	v_mfma_f32_32x32x16_bf16 v[80:95], v[174:177], v[216:219], v[80:95]
	ds_read_b64_tr_b16 v[242:243], v254 offset:0x3000
	ds_read_b64_tr_b16 v[244:245], v254 offset:0x3800
	s_waitcnt lgkmcnt(9)
	v_mfma_f32_32x32x16_bf16 v[96:111], v[178:181], v[208:211], v[96:111]
	s_waitcnt lgkmcnt(8)
	v_mfma_f32_32x32x16_bf16 v[80:95], v[2:5], v[208:211], v[80:95]
	s_and_b64 vcc, exec, s[14:15]
	s_cbranch_vccnz .LBB0_578
.Lfox_pv_go:
	s_waitcnt lgkmcnt(6)
	v_mfma_f32_32x32x16_bf16 v[64:79], v[230:233], v[140:143], v[64:79]
	ds_read_b64_tr_b16 v[2:3], v254 offset:0x200
	ds_read_b64_tr_b16 v[4:5], v254 offset:0xa00
	s_waitcnt lgkmcnt(6)
	v_mfma_f32_32x32x16_bf16 v[64:79], v[234:237], v[136:139], v[64:79]
	ds_read_b64_tr_b16 v[6:7], v254 offset:0x1200
	ds_read_b64_tr_b16 v[8:9], v254 offset:0x1a00
	s_waitcnt lgkmcnt(6)
	v_mfma_f32_32x32x16_bf16 v[64:79], v[238:241], v[132:135], v[64:79]
	ds_read_b64_tr_b16 v[10:11], v254 offset:0x2200
	ds_read_b64_tr_b16 v[12:13], v254 offset:0x2a00
	s_waitcnt lgkmcnt(6)
	v_mfma_f32_32x32x16_bf16 v[64:79], v[242:245], v[128:131], v[64:79]
	ds_read_b64_tr_b16 v[174:175], v254 offset:0x3200
	ds_read_b64_tr_b16 v[176:177], v254 offset:0x3a00
	s_waitcnt lgkmcnt(6)
	v_mfma_f32_32x32x16_bf16 v[48:63], v[2:5], v[140:143], v[48:63]
	ds_read_b64_tr_b16 v[2:3], v254 offset:0x400
	ds_read_b64_tr_b16 v[4:5], v254 offset:0xc00
	s_waitcnt lgkmcnt(6)
	v_mfma_f32_32x32x16_bf16 v[48:63], v[6:9], v[136:139], v[48:63]
	ds_read_b64_tr_b16 v[6:7], v254 offset:0x1400
	ds_read_b64_tr_b16 v[8:9], v254 offset:0x1c00
	s_waitcnt lgkmcnt(6)
	v_mfma_f32_32x32x16_bf16 v[48:63], v[10:13], v[132:135], v[48:63]
	ds_read_b64_tr_b16 v[10:11], v254 offset:0x2400
	ds_read_b64_tr_b16 v[12:13], v254 offset:0x2c00
	s_waitcnt lgkmcnt(6)
	v_mfma_f32_32x32x16_bf16 v[48:63], v[174:177], v[128:131], v[48:63]
	ds_read_b64_tr_b16 v[174:175], v254 offset:0x3400
	ds_read_b64_tr_b16 v[176:177], v254 offset:0x3c00
	s_waitcnt lgkmcnt(6)
	v_mfma_f32_32x32x16_bf16 v[32:47], v[2:5], v[140:143], v[32:47]
	ds_read_b64_tr_b16 v[2:3], v254 offset:0x600
	ds_read_b64_tr_b16 v[4:5], v254 offset:0xe00
	s_waitcnt lgkmcnt(6)
	v_mfma_f32_32x32x16_bf16 v[32:47], v[6:9], v[136:139], v[32:47]
	ds_read_b64_tr_b16 v[6:7], v254 offset:0x1600
	ds_read_b64_tr_b16 v[8:9], v254 offset:0x1e00
	s_waitcnt lgkmcnt(6)
	v_mfma_f32_32x32x16_bf16 v[32:47], v[10:13], v[132:135], v[32:47]
	ds_read_b64_tr_b16 v[10:11], v254 offset:0x2600
	ds_read_b64_tr_b16 v[12:13], v254 offset:0x2e00
	s_waitcnt lgkmcnt(6)
	v_mfma_f32_32x32x16_bf16 v[32:47], v[174:177], v[128:131], v[32:47]
	ds_read_b64_tr_b16 v[174:175], v254 offset:0x3600
	ds_read_b64_tr_b16 v[176:177], v254 offset:0x3e00
	s_waitcnt lgkmcnt(6)
	v_mfma_f32_32x32x16_bf16 v[16:31], v[2:5], v[140:143], v[16:31]
	s_waitcnt lgkmcnt(4)
	v_mfma_f32_32x32x16_bf16 v[16:31], v[6:9], v[136:139], v[16:31]
	s_waitcnt lgkmcnt(2)
	v_mfma_f32_32x32x16_bf16 v[16:31], v[10:13], v[132:135], v[16:31]
	s_waitcnt lgkmcnt(0)
	v_mfma_f32_32x32x16_bf16 v[16:31], v[174:177], v[128:131], v[16:31]

.LBB0_586:
	s_add_i32 s0, s2, 1
	s_cmp_lg_u32 s2, 2
	s_cselect_b32 s5, s0, 0
	s_add_i32 s86, s86, 64
	s_add_u32 s78, s78, 0x20000
	s_addc_u32 s79, s79, 0
	s_addk_i32 s3, 0x100
	s_add_i32 s0, s6, -1
	s_cmp_lg_u32 s0, s96
	v_subrev_u32_e32 v157, 64, v157
	s_cbranch_scc0 .LBB0_596
	s_mov_b32 s4, s2
	s_mov_b32 s6, s1
	s_mov_b32 s2, s5
	s_andn2_b64 vcc, exec, s[70:71]
	s_mov_b32 s1, s4
	s_cbranch_vccz .LBB0_569
	s_branch .LBB0_573
.LBB0_575:
	s_and_b64 vcc, exec, s[14:15]
	s_cbranch_vccnz .LBB0_578
	ds_read_b64_tr_b16 v[230:231], v254 offset:0
	ds_read_b64_tr_b16 v[232:233], v254 offset:0x800
	ds_read_b64_tr_b16 v[234:235], v254 offset:0x1000
	ds_read_b64_tr_b16 v[236:237], v254 offset:0x1800
	ds_read_b64_tr_b16 v[238:239], v254 offset:0x2000
	ds_read_b64_tr_b16 v[240:241], v254 offset:0x2800
	ds_read_b64_tr_b16 v[242:243], v254 offset:0x3000
	ds_read_b64_tr_b16 v[244:245], v254 offset:0x3800
	s_branch .Lfox_pv_go
.LBB0_588:
	s_add_i32 s6, s0, 2
	s_cmp_ge_i32 s6, s96
	s_mov_b64 s[4:5], -1
	s_cbranch_scc0 .LBB0_584
